# FFT unit stage 0: raw FNet rows fetched by LDS-DMA in full 128-byte lines (8 rows x 128 B per instruction) into a per-wave LDS ring and read back in MFMA layout, instead of 16-row x 64-B register load
# speedup vs baseline: 1.0104x; 1.0104x over previous
.LBB0_803:
	s_lshl_b32 s0, s4, 11
	s_and_b32 s7, s4, 31
	v_mov_b32_e32 v78, v0
	s_and_b32 s0, s0, 0x3800
	v_readlane_b32 s1, v252, 2
	s_add_u32 s0, s1, s0
	v_and_b32_e32 v80, 15, v78
	v_readlane_b32 s1, v252, 3
	s_addc_u32 s1, s1, 0
	v_lshlrev_b32_e32 v98, 7, v80
	s_waitcnt lgkmcnt(0)
	v_lshl_add_u64 v[2:3], s[0:1], 0, v[98:99]
	v_readlane_b32 s0, v251, 62
	v_lshlrev_b32_e32 v10, 4, v80
	v_mov_b32_e32 v11, v99
	v_readlane_b32 s1, v251, 63
	v_readlane_b32 s10, v254, 15
	v_ashrrev_i32_e32 v17, 4, v78
	v_bfe_u32 v81, v78, 4, 2
	v_lshl_add_u64 v[14:15], s[0:1], 0, v[10:11]
	v_add_u32_e32 v16, s10, v10
	v_lshlrev_b32_e32 v10, 7, v17
	v_lshlrev_b32_e32 v74, 4, v81
	v_mov_b32_e32 v75, v99
	v_ashrrev_i32_e32 v11, 31, v10
	v_lshl_add_u64 v[2:3], v[2:3], 0, v[74:75]
	v_lshl_add_u64 v[10:11], v[10:11], 1, v[14:15]
	global_load_dwordx4 v[6:9], v[2:3], off
	s_nop 0
	global_load_dwordx4 v[2:5], v[2:3], off offset:64
	v_mul_lo_u32 v17, v17, s31
	global_load_dwordx4 v[100:103], v[10:11], off
	v_add_u32_e32 v18, v16, v17
	v_add_u32_e32 v20, 0x200, v78
	v_readlane_b32 s11, v254, 16
	v_ashrrev_i32_e32 v82, 6, v78
	v_readlane_b32 s8, v252, 0
	v_readlane_b32 s9, v252, 1
	v_lshrrev_b32_e32 v83, 4, v78
	v_lshlrev_b32_e32 v79, 6, v80
	v_mov_b32_e32 v124, v18
	v_ashrrev_i32_e32 v18, 4, v20
	v_lshlrev_b32_e32 v10, 7, v18
	v_ashrrev_i32_e32 v11, 31, v10
	v_lshl_add_u64 v[10:11], v[10:11], 1, v[14:15]
	global_load_dwordx4 v[104:107], v[10:11], off
	v_mul_lo_u32 v21, v18, s31
	v_add_u32_e32 v18, v16, v21
	v_mov_b32_e32 v125, v18
	v_add_u32_e32 v10, 0x400, v78
	v_ashrrev_i32_e32 v18, 4, v10
	v_lshlrev_b32_e32 v10, 7, v18
	v_ashrrev_i32_e32 v11, 31, v10
	v_lshl_add_u64 v[10:11], v[10:11], 1, v[14:15]
	global_load_dwordx4 v[108:111], v[10:11], off
	v_mad_u64_u32 v[18:19], s[0:1], v18, s31, v[16:17]
	v_mov_b32_e32 v126, v18
	v_add_u32_e32 v10, 0x600, v78
	v_ashrrev_i32_e32 v18, 4, v10
	v_lshlrev_b32_e32 v10, 7, v18
	v_ashrrev_i32_e32 v11, 31, v10
	v_lshl_add_u64 v[10:11], v[10:11], 1, v[14:15]
	global_load_dwordx4 v[112:115], v[10:11], off
	v_mad_u64_u32 v[14:15], s[0:1], v18, s31, v[16:17]
	v_readlane_b32 s0, v252, 4
	v_readlane_b32 s1, v252, 5
	v_mov_b32_e32 v127, v14
	v_lshlrev_b32_e32 v10, 4, v78
	v_lshlrev_b32_e32 v14, 2, v78
	v_and_b32_e32 v10, 0xf0, v10
	v_ashrrev_i32_e32 v15, 31, v14
	v_add_u32_e32 v16, s11, v10
	v_lshl_add_u64 v[10:11], v[14:15], 2, s[0:1]
	global_load_dwordx4 v[116:119], v[10:11], off
	v_add_u32_e32 v15, v16, v17
	v_mov_b32_e32 v128, v15
	v_lshlrev_b32_e32 v10, 2, v20
	v_ashrrev_i32_e32 v11, 31, v10
	v_lshl_add_u64 v[10:11], v[10:11], 2, s[0:1]
	global_load_dwordx4 v[120:123], v[10:11], off
	v_add_u32_e32 v15, v16, v21
	s_and_b32 s1, s2, 0xfffff800
	s_lshl_b32 s0, s7, 4
	s_and_b32 s68, s0, 0x180
	v_mov_b32_e32 v129, v15
	s_waitcnt vmcnt(0)
	ds_write_b128 v124, v[100:103]
	ds_write_b128 v125, v[104:107]
	ds_write_b128 v126, v[108:111]
	ds_write_b128 v127, v[112:115]
	ds_write_b128 v128, v[116:119]
	ds_write_b128 v129, v[120:123]
	v_readfirstlane_b32 s22, v82
	v_and_b32_e32 v11, 63, v78
	v_lshrrev_b32_e32 v14, 3, v11
	v_and_b32_e32 v15, 7, v11
	v_xor_b32_e32 v15, v15, v14
	v_lshlrev_b32_e32 v15, 4, v15
	v_lshl_add_u32 v10, v14, 12, v15
	s_mov_b32 s38, 0x1e400
	s_lshl_b32 s23, s22, 12
	s_cmp_lt_u32 s22, 2
	s_cselect_b32 s38, 0x1dc00, s38
	s_add_i32 s23, s23, s38
	v_and_b32_e32 v14, 7, v80
	v_xor_b32_e32 v15, v81, v14
	v_lshlrev_b32_e32 v15, 4, v15
	v_lshl_add_u32 v12, v80, 7, v15
	v_add_u32_e32 v12, s23, v12
	v_or_b32_e32 v15, 4, v81
	v_xor_b32_e32 v15, v15, v14
	v_lshlrev_b32_e32 v15, 4, v15
	v_lshl_add_u32 v13, v80, 7, v15
	v_add_u32_e32 v13, s23, v13
	v_lshlrev_b32_e32 v14, 3, v78
	v_and_b32_e32 v84, 0x80, v14
	v_lshlrev_b32_e32 v14, 2, v78
	v_and_b32_e32 v14, 0x80, v14
	v_lshl_add_u32 v85, v82, 4, v14
	v_or_b32_e32 v72, 16, v80
	v_or_b32_e32 v14, 0x0, v80
	v_or_b32_e32 v14, v84, v14
	v_mad_u32_u24 v62, v14, s31, v85
	v_or_b32_e32 v14, 0x20, v80
	v_or_b32_e32 v14, v84, v14
	v_mad_u32_u24 v63, v14, s31, v85
	v_or_b32_e32 v14, 0x40, v80
	v_or_b32_e32 v14, v84, v14
	v_mad_u32_u24 v64, v14, s31, v85
	v_or_b32_e32 v14, 0x60, v80
	v_or_b32_e32 v14, v84, v14
	v_mad_u32_u24 v65, v14, s31, v85
	v_or_b32_e32 v14, 0x0, v72
	v_or_b32_e32 v14, v84, v14
	v_mad_u32_u24 v66, v14, s31, v85
	v_or_b32_e32 v14, 0x20, v72
	v_or_b32_e32 v14, v84, v14
	v_mad_u32_u24 v67, v14, s31, v85
	v_or_b32_e32 v14, 0x40, v72
	v_or_b32_e32 v14, v84, v14
	v_mad_u32_u24 v68, v14, s31, v85
	v_or_b32_e32 v14, 0x60, v72
	v_or_b32_e32 v14, v84, v14
	v_mad_u32_u24 v69, v14, s31, v85
	s_lshl_b32 s38, s22, 8
	s_add_i32 s38, s38, s1
	s_lshl_b32 s38, s38, 12
	s_add_u32 s38, s86, s38
	s_addc_u32 s39, s87, 0
	s_add_u32 s38, s38, s68
	s_addc_u32 s39, s39, s69
	s_add_u32 s38, s38, s95
	s_addc_u32 s39, s39, 0
	s_add_u32 s38, s38, 0x600
	s_addc_u32 s39, s39, 0
	s_add_i32 m0, s23, 0x0
	s_add_u32 s100, s38, 0x8000
	s_addc_u32 s101, s39, 0
	global_load_lds_dwordx4 v10, s[38:39]
	s_add_i32 m0, s23, 0x400
	s_add_u32 s38, s38, 0x10000
	global_load_lds_dwordx4 v10, s[100:101]
	s_addc_u32 s39, s39, 0
	s_add_i32 m0, s23, 0x800
	s_add_u32 s100, s38, 0x8000
	s_addc_u32 s101, s39, 0
	global_load_lds_dwordx4 v10, s[38:39]
	s_add_i32 m0, s23, 0xc00
	s_add_u32 s38, s38, 0x10000
	global_load_lds_dwordx4 v10, s[100:101]
	s_addc_u32 s39, s39, 0
	s_waitcnt vmcnt(2)
	ds_read_b128 v[14:17], v12
	ds_read_b128 v[18:21], v13
	s_waitcnt lgkmcnt(0)
	s_add_i32 m0, s23, 0x0
	s_add_u32 s100, s38, 0x8000
	s_addc_u32 s101, s39, 0
	global_load_lds_dwordx4 v10, s[38:39]
	s_add_i32 m0, s23, 0x400
	s_add_u32 s38, s38, 0x10000
	global_load_lds_dwordx4 v10, s[100:101]
	s_addc_u32 s39, s39, 0
	v_mfma_f32_16x16x32_bf16 v[30:33], v[6:9], v[14:17], 0
	v_mfma_f32_16x16x32_bf16 v[30:33], v[2:5], v[18:21], v[30:33]
	s_waitcnt vmcnt(2)
	ds_read_b128 v[22:25], v12 offset:2048
	ds_read_b128 v[26:29], v13 offset:2048
	s_waitcnt lgkmcnt(0)
	s_add_i32 m0, s23, 0x800
	s_add_u32 s100, s38, 0x8000
	s_addc_u32 s101, s39, 0
	global_load_lds_dwordx4 v10, s[38:39]
	s_add_i32 m0, s23, 0xc00
	s_add_u32 s38, s38, 0x10000
	global_load_lds_dwordx4 v10, s[100:101]
	s_addc_u32 s39, s39, 0
	v_mfma_f32_16x16x32_bf16 v[34:37], v[6:9], v[22:25], 0
	v_mfma_f32_16x16x32_bf16 v[34:37], v[2:5], v[26:29], v[34:37]
	s_waitcnt vmcnt(2)
	ds_read_b128 v[14:17], v12
	ds_read_b128 v[18:21], v13
	s_waitcnt lgkmcnt(0)
	s_add_i32 m0, s23, 0x0
	s_add_u32 s100, s38, 0x8000
	s_addc_u32 s101, s39, 0
	global_load_lds_dwordx4 v10, s[38:39]
	s_add_i32 m0, s23, 0x400
	s_add_u32 s38, s38, 0x10000
	global_load_lds_dwordx4 v10, s[100:101]
	s_addc_u32 s39, s39, 0
	v_mfma_f32_16x16x32_bf16 v[38:41], v[6:9], v[14:17], 0
	v_mfma_f32_16x16x32_bf16 v[38:41], v[2:5], v[18:21], v[38:41]
	s_waitcnt vmcnt(2)
	ds_read_b128 v[22:25], v12 offset:2048
	ds_read_b128 v[26:29], v13 offset:2048
	s_waitcnt lgkmcnt(0)
	s_add_i32 m0, s23, 0x800
	s_add_u32 s100, s38, 0x8000
	s_addc_u32 s101, s39, 0
	global_load_lds_dwordx4 v10, s[38:39]
	s_add_i32 m0, s23, 0xc00
	s_add_u32 s38, s38, 0x10000
	global_load_lds_dwordx4 v10, s[100:101]
	s_addc_u32 s39, s39, 0
	v_mfma_f32_16x16x32_bf16 v[42:45], v[6:9], v[22:25], 0
	v_mfma_f32_16x16x32_bf16 v[42:45], v[2:5], v[26:29], v[42:45]
	s_waitcnt vmcnt(2)
	ds_read_b128 v[14:17], v12
	ds_read_b128 v[18:21], v13
	s_waitcnt lgkmcnt(0)
	s_add_i32 m0, s23, 0x0
	s_add_u32 s100, s38, 0x8000
	s_addc_u32 s101, s39, 0
	global_load_lds_dwordx4 v10, s[38:39]
	s_add_i32 m0, s23, 0x400
	s_add_u32 s38, s38, 0x10000
	global_load_lds_dwordx4 v10, s[100:101]
	s_addc_u32 s39, s39, 0
	v_mfma_f32_16x16x32_bf16 v[46:49], v[6:9], v[14:17], 0
	v_mfma_f32_16x16x32_bf16 v[46:49], v[2:5], v[18:21], v[46:49]
	s_waitcnt vmcnt(2)
	ds_read_b128 v[22:25], v12 offset:2048
	ds_read_b128 v[26:29], v13 offset:2048
	s_waitcnt lgkmcnt(0)
	s_add_i32 m0, s23, 0x800
	s_add_u32 s100, s38, 0x8000
	s_addc_u32 s101, s39, 0
	global_load_lds_dwordx4 v10, s[38:39]
	s_add_i32 m0, s23, 0xc00
	s_add_u32 s38, s38, 0x10000
	global_load_lds_dwordx4 v10, s[100:101]
	s_addc_u32 s39, s39, 0
	v_mfma_f32_16x16x32_bf16 v[50:53], v[6:9], v[22:25], 0
	v_mfma_f32_16x16x32_bf16 v[50:53], v[2:5], v[26:29], v[50:53]
	s_waitcnt vmcnt(2)
	ds_read_b128 v[14:17], v12
	ds_read_b128 v[18:21], v13
	s_waitcnt lgkmcnt(0)
	s_add_i32 m0, s23, 0x0
	s_add_u32 s100, s38, 0x8000
	s_addc_u32 s101, s39, 0
	global_load_lds_dwordx4 v10, s[38:39]
	s_add_i32 m0, s23, 0x400
	s_add_u32 s38, s38, 0x10000
	global_load_lds_dwordx4 v10, s[100:101]
	s_addc_u32 s39, s39, 0
	v_mfma_f32_16x16x32_bf16 v[54:57], v[6:9], v[14:17], 0
	v_mfma_f32_16x16x32_bf16 v[54:57], v[2:5], v[18:21], v[54:57]
	s_waitcnt vmcnt(2)
	ds_read_b128 v[22:25], v12 offset:2048
	ds_read_b128 v[26:29], v13 offset:2048
	s_waitcnt lgkmcnt(0)
	s_add_i32 m0, s23, 0x800
	s_add_u32 s100, s38, 0x8000
	s_addc_u32 s101, s39, 0
	global_load_lds_dwordx4 v10, s[38:39]
	s_add_i32 m0, s23, 0xc00
	s_add_u32 s38, s38, 0x10000
	global_load_lds_dwordx4 v10, s[100:101]
	s_addc_u32 s39, s39, 0
	v_mfma_f32_16x16x32_bf16 v[58:61], v[6:9], v[22:25], 0
	v_mfma_f32_16x16x32_bf16 v[58:61], v[2:5], v[26:29], v[58:61]
	s_nop 7
	s_nop 3
	v_cvt_pk_bf16_f32 v86, v30, v38
	v_cvt_pk_bf16_f32 v87, v46, v54
	ds_write_b64 v62, v[86:87]
	v_cvt_pk_bf16_f32 v88, v31, v39
	v_cvt_pk_bf16_f32 v89, v47, v55
	ds_write_b64 v63, v[88:89]
	v_cvt_pk_bf16_f32 v86, v32, v40
	v_cvt_pk_bf16_f32 v87, v48, v56
	ds_write_b64 v64, v[86:87]
	v_cvt_pk_bf16_f32 v88, v33, v41
	v_cvt_pk_bf16_f32 v89, v49, v57
	ds_write_b64 v65, v[88:89]
	v_cvt_pk_bf16_f32 v86, v34, v42
	v_cvt_pk_bf16_f32 v87, v50, v58
	ds_write_b64 v66, v[86:87]
	v_cvt_pk_bf16_f32 v88, v35, v43
	v_cvt_pk_bf16_f32 v89, v51, v59
	ds_write_b64 v67, v[88:89]
	v_cvt_pk_bf16_f32 v86, v36, v44
	v_cvt_pk_bf16_f32 v87, v52, v60
	ds_write_b64 v68, v[86:87]
	v_cvt_pk_bf16_f32 v88, v37, v45
	v_cvt_pk_bf16_f32 v89, v53, v61
	ds_write_b64 v69, v[88:89]
	s_waitcnt vmcnt(2)
	ds_read_b128 v[14:17], v12
	ds_read_b128 v[18:21], v13
	s_waitcnt lgkmcnt(0)
	s_add_i32 m0, s23, 0x0
	s_add_u32 s100, s38, 0x8000
	s_addc_u32 s101, s39, 0
	global_load_lds_dwordx4 v10, s[38:39]
	s_add_i32 m0, s23, 0x400
	s_add_u32 s38, s38, 0x10000
	global_load_lds_dwordx4 v10, s[100:101]
	s_addc_u32 s39, s39, 0
	v_mfma_f32_16x16x32_bf16 v[30:33], v[6:9], v[14:17], 0
	v_mfma_f32_16x16x32_bf16 v[30:33], v[2:5], v[18:21], v[30:33]
	s_waitcnt vmcnt(2)
	ds_read_b128 v[22:25], v12 offset:2048
	ds_read_b128 v[26:29], v13 offset:2048
	s_waitcnt lgkmcnt(0)
	s_add_i32 m0, s23, 0x800
	s_add_u32 s100, s38, 0x8000
	s_addc_u32 s101, s39, 0
	global_load_lds_dwordx4 v10, s[38:39]
	s_add_i32 m0, s23, 0xc00
	s_add_u32 s38, s38, 0x10000
	global_load_lds_dwordx4 v10, s[100:101]
	s_addc_u32 s39, s39, 0
	v_mfma_f32_16x16x32_bf16 v[34:37], v[6:9], v[22:25], 0
	v_mfma_f32_16x16x32_bf16 v[34:37], v[2:5], v[26:29], v[34:37]
	s_waitcnt vmcnt(2)
	ds_read_b128 v[14:17], v12
	ds_read_b128 v[18:21], v13
	s_waitcnt lgkmcnt(0)
	s_add_i32 m0, s23, 0x0
	s_add_u32 s100, s38, 0x8000
	s_addc_u32 s101, s39, 0
	global_load_lds_dwordx4 v10, s[38:39]
	s_add_i32 m0, s23, 0x400
	s_add_u32 s38, s38, 0x10000
	global_load_lds_dwordx4 v10, s[100:101]
	s_addc_u32 s39, s39, 0
	v_mfma_f32_16x16x32_bf16 v[38:41], v[6:9], v[14:17], 0
	v_mfma_f32_16x16x32_bf16 v[38:41], v[2:5], v[18:21], v[38:41]
	s_waitcnt vmcnt(2)
	ds_read_b128 v[22:25], v12 offset:2048
	ds_read_b128 v[26:29], v13 offset:2048
	s_waitcnt lgkmcnt(0)
	s_add_i32 m0, s23, 0x800
	s_add_u32 s100, s38, 0x8000
	s_addc_u32 s101, s39, 0
	global_load_lds_dwordx4 v10, s[38:39]
	s_add_i32 m0, s23, 0xc00
	s_add_u32 s38, s38, 0x10000
	global_load_lds_dwordx4 v10, s[100:101]
	s_addc_u32 s39, s39, 0
	v_mfma_f32_16x16x32_bf16 v[42:45], v[6:9], v[22:25], 0
	v_mfma_f32_16x16x32_bf16 v[42:45], v[2:5], v[26:29], v[42:45]
	s_waitcnt vmcnt(2)
	ds_read_b128 v[14:17], v12
	ds_read_b128 v[18:21], v13
	s_waitcnt lgkmcnt(0)
	s_add_i32 m0, s23, 0x0
	s_add_u32 s100, s38, 0x8000
	s_addc_u32 s101, s39, 0
	global_load_lds_dwordx4 v10, s[38:39]
	s_add_i32 m0, s23, 0x400
	s_add_u32 s38, s38, 0x10000
	global_load_lds_dwordx4 v10, s[100:101]
	s_addc_u32 s39, s39, 0
	v_mfma_f32_16x16x32_bf16 v[46:49], v[6:9], v[14:17], 0
	v_mfma_f32_16x16x32_bf16 v[46:49], v[2:5], v[18:21], v[46:49]
	s_waitcnt vmcnt(2)
	ds_read_b128 v[22:25], v12 offset:2048
	ds_read_b128 v[26:29], v13 offset:2048
	s_waitcnt lgkmcnt(0)
	s_add_i32 m0, s23, 0x800
	s_add_u32 s100, s38, 0x8000
	s_addc_u32 s101, s39, 0
	global_load_lds_dwordx4 v10, s[38:39]
	s_add_i32 m0, s23, 0xc00
	s_add_u32 s38, s38, 0x10000
	global_load_lds_dwordx4 v10, s[100:101]
	s_addc_u32 s39, s39, 0
	v_mfma_f32_16x16x32_bf16 v[50:53], v[6:9], v[22:25], 0
	v_mfma_f32_16x16x32_bf16 v[50:53], v[2:5], v[26:29], v[50:53]
	s_waitcnt vmcnt(2)
	ds_read_b128 v[14:17], v12
	ds_read_b128 v[18:21], v13
	s_waitcnt lgkmcnt(0)
	v_mfma_f32_16x16x32_bf16 v[54:57], v[6:9], v[14:17], 0
	v_mfma_f32_16x16x32_bf16 v[54:57], v[2:5], v[18:21], v[54:57]
	s_waitcnt vmcnt(0)
	ds_read_b128 v[22:25], v12 offset:2048
	ds_read_b128 v[26:29], v13 offset:2048
	s_waitcnt lgkmcnt(0)
	v_mfma_f32_16x16x32_bf16 v[58:61], v[6:9], v[22:25], 0
	v_mfma_f32_16x16x32_bf16 v[58:61], v[2:5], v[26:29], v[58:61]
	s_nop 7
	s_nop 3
	v_cvt_pk_bf16_f32 v86, v30, v38
	v_cvt_pk_bf16_f32 v87, v46, v54
	ds_write_b64 v62, v[86:87] offset:8
	v_cvt_pk_bf16_f32 v88, v31, v39
	v_cvt_pk_bf16_f32 v89, v47, v55
	ds_write_b64 v63, v[88:89] offset:8
	v_cvt_pk_bf16_f32 v86, v32, v40
	v_cvt_pk_bf16_f32 v87, v48, v56
	ds_write_b64 v64, v[86:87] offset:8
	v_cvt_pk_bf16_f32 v88, v33, v41
	v_cvt_pk_bf16_f32 v89, v49, v57
	ds_write_b64 v65, v[88:89] offset:8
	v_cvt_pk_bf16_f32 v86, v34, v42
	v_cvt_pk_bf16_f32 v87, v50, v58
	ds_write_b64 v66, v[86:87] offset:8
	v_cvt_pk_bf16_f32 v88, v35, v43
	v_cvt_pk_bf16_f32 v89, v51, v59
	ds_write_b64 v67, v[88:89] offset:8
	v_cvt_pk_bf16_f32 v86, v36, v44
	v_cvt_pk_bf16_f32 v87, v52, v60
	ds_write_b64 v68, v[86:87] offset:8
	v_cvt_pk_bf16_f32 v88, v37, v45
	v_cvt_pk_bf16_f32 v89, v53, v61
	ds_write_b64 v69, v[88:89] offset:8
	v_lshl_or_b32 v18, v82, 5, v80
	v_mul_lo_u32 v18, v18, s31
	v_mov_b32_e32 v36, 0x1100
	s_nop 0
	v_mov_b32_e32 v44, 0x2200
	v_mov_b32_e32 v53, 0x3300
	v_lshl_add_u64 v[2:3], s[8:9], 0, v[74:75]
	v_add3_u32 v31, 0, v18, v74
	v_add_u32_e32 v52, s10, v74
	v_mad_u32_u24 v75, v80, s31, v36
	v_mad_u32_u24 v74, v80, s31, v44
	v_mad_u32_u24 v73, v80, s31, v53
	v_lshl_add_u64 v[2:3], v[2:3], 0, v[98:99]
	v_mad_u32_u24 v30, v80, s31, v52
	v_add_u32_e32 v76, v52, v75
	v_add_u32_e32 v77, v52, v74
	v_add_u32_e32 v96, v52, v73
	global_load_dwordx4 v[10:13], v[2:3], off
	global_load_dwordx4 v[6:9], v[2:3], off offset:64
	global_load_dwordx4 v[14:17], v[2:3], off offset:2048
	s_nop 0
	global_load_dwordx4 v[2:5], v[2:3], off offset:2112
	s_waitcnt lgkmcnt(0)
	s_barrier
	ds_read_b128 v[18:21], v31
	ds_read_b128 v[22:25], v31 offset:4352
	ds_read_b128 v[26:29], v30
	ds_read_b128 v[60:63], v30 offset:17408
	ds_read_b128 v[36:39], v76
	ds_read_b128 v[100:103], v30 offset:30464
	ds_read_b128 v[44:47], v77
	ds_read_b128 v[52:55], v96
	ds_read_b128 v[68:71], v30 offset:21760
	ds_read_b128 v[88:91], v30 offset:26112
	s_waitcnt lgkmcnt(7)
	v_mfma_f32_16x16x32_bf16 v[32:35], v[18:21], v[26:29], 0
	s_movk_i32 s10, 0x90
	v_bfe_u32 v98, v78, 1, 3
	v_mfma_f32_16x16x32_bf16 v[26:29], v[22:25], v[26:29], 0
	s_waitcnt lgkmcnt(5)
	v_mfma_f32_16x16x32_bf16 v[40:43], v[18:21], v[36:39], 0
	v_mfma_f32_16x16x32_bf16 v[36:39], v[22:25], v[36:39], 0
	s_waitcnt lgkmcnt(3)
	v_mfma_f32_16x16x32_bf16 v[48:51], v[18:21], v[44:47], 0
	v_mfma_f32_16x16x32_bf16 v[44:47], v[22:25], v[44:47], 0
	s_waitcnt lgkmcnt(2)
	v_mfma_f32_16x16x32_bf16 v[56:59], v[18:21], v[52:55], 0
	v_mfma_f32_16x16x32_bf16 v[52:55], v[22:25], v[52:55], 0
	v_mfma_f32_16x16x32_bf16 v[64:67], v[18:21], v[60:63], 0
	v_mfma_f32_16x16x32_bf16 v[60:63], v[22:25], v[60:63], 0
	s_waitcnt lgkmcnt(1)
	v_mfma_f32_16x16x32_bf16 v[84:87], v[18:21], v[68:71], 0
	v_mfma_f32_16x16x32_bf16 v[68:71], v[22:25], v[68:71], 0
	s_waitcnt lgkmcnt(0)
	v_mfma_f32_16x16x32_bf16 v[92:95], v[18:21], v[88:91], 0
	v_mfma_f32_16x16x32_bf16 v[88:91], v[22:25], v[88:91], 0
	v_mfma_f32_16x16x32_bf16 v[18:21], v[18:21], v[100:103], 0
	v_mfma_f32_16x16x32_bf16 v[22:25], v[22:25], v[100:103], 0
	ds_read_b128 v[100:103], v31 offset:64
	ds_read_b128 v[104:107], v31 offset:4416
	ds_read_b128 v[108:111], v30 offset:64
	s_waitcnt lgkmcnt(0)
	v_mfma_f32_16x16x32_bf16 v[32:35], v[100:103], v[108:111], v[32:35]
	v_mfma_f32_16x16x32_bf16 v[26:29], v[104:107], v[108:111], v[26:29]
	ds_read_b128 v[108:111], v76 offset:64
	s_waitcnt lgkmcnt(0)
	v_mfma_f32_16x16x32_bf16 v[40:43], v[100:103], v[108:111], v[40:43]
	v_mfma_f32_16x16x32_bf16 v[36:39], v[104:107], v[108:111], v[36:39]
	ds_read_b128 v[108:111], v77 offset:64
	s_waitcnt lgkmcnt(0)
	v_mfma_f32_16x16x32_bf16 v[48:51], v[100:103], v[108:111], v[48:51]
	v_mfma_f32_16x16x32_bf16 v[44:47], v[104:107], v[108:111], v[44:47]
	ds_read_b128 v[108:111], v96 offset:64
	s_waitcnt lgkmcnt(0)
	v_mfma_f32_16x16x32_bf16 v[56:59], v[100:103], v[108:111], v[56:59]
	v_mfma_f32_16x16x32_bf16 v[52:55], v[104:107], v[108:111], v[52:55]
	ds_read_b128 v[108:111], v30 offset:17472
	s_waitcnt lgkmcnt(0)
	v_mfma_f32_16x16x32_bf16 v[64:67], v[100:103], v[108:111], v[64:67]
	v_mfma_f32_16x16x32_bf16 v[60:63], v[104:107], v[108:111], v[60:63]
	ds_read_b128 v[108:111], v30 offset:21824
	s_waitcnt lgkmcnt(0)
	v_mfma_f32_16x16x32_bf16 v[84:87], v[100:103], v[108:111], v[84:87]
	v_mfma_f32_16x16x32_bf16 v[68:71], v[104:107], v[108:111], v[68:71]
	ds_read_b128 v[108:111], v30 offset:26176
	s_waitcnt lgkmcnt(0)
	v_mfma_f32_16x16x32_bf16 v[92:95], v[100:103], v[108:111], v[92:95]
	v_mfma_f32_16x16x32_bf16 v[88:91], v[104:107], v[108:111], v[88:91]
	ds_read_b128 v[108:111], v30 offset:30528
	s_waitcnt lgkmcnt(0)
	v_mfma_f32_16x16x32_bf16 v[18:21], v[100:103], v[108:111], v[18:21]
	v_mfma_f32_16x16x32_bf16 v[22:25], v[104:107], v[108:111], v[22:25]
	ds_read_b128 v[100:103], v31 offset:128
	ds_read_b128 v[104:107], v31 offset:4480
	ds_read_b128 v[108:111], v30 offset:128
	s_waitcnt lgkmcnt(0)
	v_mfma_f32_16x16x32_bf16 v[32:35], v[100:103], v[108:111], v[32:35]
	v_mfma_f32_16x16x32_bf16 v[26:29], v[104:107], v[108:111], v[26:29]
	ds_read_b128 v[108:111], v76 offset:128
	s_waitcnt lgkmcnt(0)
	v_mfma_f32_16x16x32_bf16 v[40:43], v[100:103], v[108:111], v[40:43]
	v_mfma_f32_16x16x32_bf16 v[36:39], v[104:107], v[108:111], v[36:39]
	ds_read_b128 v[108:111], v77 offset:128
	s_waitcnt lgkmcnt(0)
	v_mfma_f32_16x16x32_bf16 v[112:115], v[100:103], v[108:111], v[48:51]
	v_mfma_f32_16x16x32_bf16 v[46:49], v[104:107], v[108:111], v[44:47]
	ds_read_b128 v[108:111], v96 offset:128
	s_waitcnt lgkmcnt(0)
	v_mfma_f32_16x16x32_bf16 v[56:59], v[100:103], v[108:111], v[56:59]
	v_mfma_f32_16x16x32_bf16 v[108:111], v[104:107], v[108:111], v[52:55]
	s_nop 2
	ds_read_b128 v[50:53], v30 offset:17536
	s_waitcnt lgkmcnt(0)
	v_mfma_f32_16x16x32_bf16 v[116:119], v[100:103], v[50:53], v[64:67]
	v_mfma_f32_16x16x32_bf16 v[120:123], v[104:107], v[50:53], v[60:63]
	ds_read_b128 v[50:53], v30 offset:21888
	s_waitcnt lgkmcnt(0)
	v_mfma_f32_16x16x32_bf16 v[84:87], v[100:103], v[50:53], v[84:87]
	v_mfma_f32_16x16x32_bf16 v[124:127], v[104:107], v[50:53], v[68:71]
	ds_read_b128 v[50:53], v30 offset:26240
	s_waitcnt lgkmcnt(0)
	v_mfma_f32_16x16x32_bf16 v[92:95], v[100:103], v[50:53], v[92:95]
	v_mfma_f32_16x16x32_bf16 v[88:91], v[104:107], v[50:53], v[88:91]
	ds_read_b128 v[50:53], v30 offset:30592
	s_waitcnt lgkmcnt(0)
	v_mfma_f32_16x16x32_bf16 v[100:103], v[100:103], v[50:53], v[18:21]
	ds_read_b128 v[128:131], v31 offset:192
	ds_read_b128 v[132:135], v31 offset:4544
	s_nop 0
	ds_read_b128 v[18:21], v30 offset:192
	s_waitcnt lgkmcnt(0)
	v_mfma_f32_16x16x32_bf16 v[136:139], v[128:131], v[18:21], v[32:35]
	v_mfma_f32_16x16x32_bf16 v[62:65], v[132:135], v[18:21], v[26:29]
	ds_read_b128 v[18:21], v76 offset:192
	v_bfe_u32 v76, v83, 1, 1
	v_mfma_f32_16x16x32_bf16 v[104:107], v[104:107], v[50:53], v[22:25]
	s_waitcnt lgkmcnt(0)
	v_mfma_f32_16x16x32_bf16 v[50:53], v[128:131], v[18:21], v[40:43]
	v_mfma_f32_16x16x32_bf16 v[42:45], v[132:135], v[18:21], v[36:39]
	ds_read_b128 v[18:21], v77 offset:192
	s_nop 1
	ds_read_b128 v[38:41], v30 offset:17600
	s_waitcnt lgkmcnt(1)
	v_mfma_f32_16x16x32_bf16 v[34:37], v[128:131], v[18:21], v[112:115]
	v_lshl_add_u32 v77, v81, 5, s11
	v_mad_u32_u24 v83, v80, s31, v77
	v_add_u32_e32 v75, v77, v75
	v_mfma_f32_16x16x32_bf16 v[26:29], v[132:135], v[18:21], v[46:49]
	ds_read_b128 v[18:21], v96 offset:192
	s_waitcnt lgkmcnt(0)
	v_mfma_f32_16x16x32_bf16 v[22:25], v[128:131], v[18:21], v[56:59]
	v_mfma_f32_16x16x32_bf16 v[18:21], v[132:135], v[18:21], v[108:111]
	v_mfma_f32_16x16x32_bf16 v[108:111], v[128:131], v[38:41], v[116:119]
	v_mfma_f32_16x16x32_bf16 v[112:115], v[132:135], v[38:41], v[120:123]
	ds_read_b128 v[38:41], v30 offset:21952
	s_waitcnt lgkmcnt(0)
	v_mfma_f32_16x16x32_bf16 v[66:69], v[128:131], v[38:41], v[84:87]
	v_mfma_f32_16x16x32_bf16 v[58:61], v[132:135], v[38:41], v[124:127]
	ds_read_b128 v[38:41], v30 offset:26304
	ds_read_b128 v[30:33], v30 offset:30656
	s_waitcnt lgkmcnt(0)
	v_mfma_f32_16x16x32_bf16 v[46:49], v[132:135], v[38:41], v[88:91]
	s_barrier
	ds_read_b128 v[84:87], v83
	s_nop 0
	ds_read_b128 v[88:91], v83 offset:16
	v_mfma_f32_16x16x32_bf16 v[54:57], v[128:131], v[38:41], v[92:95]
	s_waitcnt lgkmcnt(0)
	v_mov_b32_e32 v97, v90
	s_nop 0
	v_lshrrev_b32_e32 v93, 1, v78
	v_mov_b32_e32 v95, v86
	v_mov_b32_e32 v86, v85
	v_mov_b32_e32 v90, v89
	v_and_b32_e32 v70, 8, v93
	v_mov_b32_e32 v94, v84
	v_pk_mul_f32 v[84:85], v[108:109], v[86:87]
	v_mov_b32_e32 v96, v88
	v_pk_mul_f32 v[88:89], v[110:111], v[90:91]
	v_add_u32_e32 v92, 0, v70
	v_lshl_add_u32 v70, v80, 3, v82
	v_pk_fma_f32 v[84:85], v[136:137], v[94:95], v[84:85] neg_lo:[0,0,1] neg_hi:[0,0,1]
	v_pk_fma_f32 v[88:89], v[138:139], v[96:97], v[88:89] neg_lo:[0,0,1] neg_hi:[0,0,1]
	v_mad_u64_u32 v[70:71], s[8:9], v70, s10, v[92:93]
	v_cvt_pk_bf16_f32 v84, v84, v85
	v_cvt_pk_bf16_f32 v85, v88, v89
	v_pk_mul_f32 v[88:89], v[108:109], v[94:95]
	v_bitop3_b32 v71, v76, v93, 7 bitop3:0x78
	v_pk_fma_f32 v[86:87], v[136:137], v[86:87], v[88:89]
	v_pk_mul_f32 v[88:89], v[110:111], v[96:97]
	v_lshlrev_b32_e32 v71, 4, v71
	v_pk_fma_f32 v[88:89], v[138:139], v[90:91], v[88:89]
	v_cvt_pk_bf16_f32 v86, v86, v87
	v_cvt_pk_bf16_f32 v87, v88, v89
	v_add_u32_e32 v88, v70, v71
	ds_write_b64 v88, v[84:85]
	v_bitop3_b32 v84, v76, v98, 4 bitop3:0x36
	v_mfma_f32_16x16x32_bf16 v[38:41], v[128:131], v[30:33], v[100:103]
	s_nop 2
	v_lshlrev_b32_e32 v100, 4, v84
	v_add_u32_e32 v84, v70, v100
	ds_write_b64 v84, v[86:87]
	ds_read_b128 v[84:87], v83 offset:128
	ds_read_b128 v[88:91], v83 offset:144
	v_mfma_f32_16x16x32_bf16 v[30:33], v[132:135], v[30:33], v[104:107]
	s_waitcnt lgkmcnt(1)
	v_mov_b32_e32 v95, v86
	v_mov_b32_e32 v86, v85
	s_waitcnt lgkmcnt(0)
	v_mov_b32_e32 v97, v90
	v_mov_b32_e32 v90, v89
	v_mov_b32_e32 v94, v84
	v_pk_mul_f32 v[84:85], v[112:113], v[86:87]
	v_mov_b32_e32 v96, v88
	v_pk_mul_f32 v[88:89], v[114:115], v[90:91]
	v_pk_fma_f32 v[84:85], v[62:63], v[94:95], v[84:85] neg_lo:[0,0,1] neg_hi:[0,0,1]
	v_pk_fma_f32 v[88:89], v[64:65], v[96:97], v[88:89] neg_lo:[0,0,1] neg_hi:[0,0,1]
	v_cvt_pk_bf16_f32 v84, v84, v85
	v_cvt_pk_bf16_f32 v85, v88, v89
	v_pk_mul_f32 v[88:89], v[112:113], v[94:95]
	s_nop 0
	v_pk_fma_f32 v[62:63], v[62:63], v[86:87], v[88:89]
	v_pk_mul_f32 v[86:87], v[114:115], v[96:97]
	v_cvt_pk_bf16_f32 v62, v62, v63
	v_pk_fma_f32 v[64:65], v[64:65], v[90:91], v[86:87]
	s_nop 0
	v_cvt_pk_bf16_f32 v63, v64, v65
	v_bitop3_b32 v64, v76, v98, 2 bitop3:0x36
	v_lshlrev_b32_e32 v83, 4, v64
	v_add_u32_e32 v64, v70, v83
	ds_write_b64 v64, v[84:85]
	v_bitop3_b32 v64, v76, v98, 6 bitop3:0x36
	v_lshlrev_b32_e32 v94, 4, v64
	v_add_u32_e32 v64, v70, v94
	ds_write_b64 v64, v[62:63]
	v_lshl_add_u32 v62, v72, 3, v82
	v_mad_u64_u32 v[88:89], s[8:9], v62, s10, v[92:93]
	ds_read_b128 v[62:65], v75
	ds_read_b128 v[84:87], v75 offset:16
	s_waitcnt lgkmcnt(1)
	v_mov_b32_e32 v90, v62
	v_mov_b32_e32 v91, v64
	v_mov_b32_e32 v64, v63
	v_pk_mul_f32 v[62:63], v[66:67], v[64:65]
	s_waitcnt lgkmcnt(0)
	v_mov_b32_e32 v92, v84
	v_mov_b32_e32 v93, v86
	v_mov_b32_e32 v86, v85
	v_pk_mul_f32 v[66:67], v[66:67], v[90:91]
	v_pk_fma_f32 v[62:63], v[50:51], v[90:91], v[62:63] neg_lo:[0,0,1] neg_hi:[0,0,1]
	v_pk_mul_f32 v[84:85], v[68:69], v[86:87]
	v_pk_fma_f32 v[50:51], v[50:51], v[64:65], v[66:67]
	v_pk_mul_f32 v[64:65], v[68:69], v[92:93]
	v_pk_fma_f32 v[84:85], v[52:53], v[92:93], v[84:85] neg_lo:[0,0,1] neg_hi:[0,0,1]
	v_pk_fma_f32 v[52:53], v[52:53], v[86:87], v[64:65]
	v_cvt_pk_bf16_f32 v62, v62, v63
	v_cvt_pk_bf16_f32 v63, v84, v85
	v_cvt_pk_bf16_f32 v50, v50, v51
	v_cvt_pk_bf16_f32 v51, v52, v53
	v_add_u32_e32 v52, v88, v71
	ds_write_b64 v52, v[62:63]
	v_add_u32_e32 v52, v88, v100
	ds_write_b64 v52, v[50:51]
	ds_read_b128 v[50:53], v75 offset:128
	ds_read_b128 v[62:65], v75 offset:144
	s_waitcnt lgkmcnt(1)
	v_mov_b32_e32 v66, v50
	v_mov_b32_e32 v67, v52
	v_mov_b32_e32 v52, v51
	v_pk_mul_f32 v[50:51], v[58:59], v[52:53]
	s_waitcnt lgkmcnt(0)
	v_mov_b32_e32 v68, v62
	v_mov_b32_e32 v69, v64
	v_mov_b32_e32 v64, v63
	v_pk_mul_f32 v[58:59], v[58:59], v[66:67]
	v_pk_fma_f32 v[50:51], v[42:43], v[66:67], v[50:51] neg_lo:[0,0,1] neg_hi:[0,0,1]
	v_pk_mul_f32 v[62:63], v[60:61], v[64:65]
	v_pk_fma_f32 v[42:43], v[42:43], v[52:53], v[58:59]
	v_pk_mul_f32 v[52:53], v[60:61], v[68:69]
	v_pk_fma_f32 v[62:63], v[44:45], v[68:69], v[62:63] neg_lo:[0,0,1] neg_hi:[0,0,1]
	v_pk_fma_f32 v[44:45], v[44:45], v[64:65], v[52:53]
	v_cvt_pk_bf16_f32 v50, v50, v51
	v_cvt_pk_bf16_f32 v51, v62, v63
	v_cvt_pk_bf16_f32 v42, v42, v43
	v_cvt_pk_bf16_f32 v43, v44, v45
	v_add_u32_e32 v44, v88, v83
	ds_write_b64 v44, v[50:51]
	v_add_u32_e32 v44, v88, v94
	ds_write_b64 v44, v[42:43]
	v_add_u32_e32 v62, v77, v74
	ds_read_b128 v[42:45], v62
	ds_read_b128 v[50:53], v62 offset:16
	v_add_u32_e32 v63, 0x9000, v70
	s_waitcnt lgkmcnt(1)
	v_mov_b32_e32 v59, v44
	v_mov_b32_e32 v44, v43
	s_waitcnt lgkmcnt(0)
	v_mov_b32_e32 v61, v52
	v_mov_b32_e32 v52, v51
	v_mov_b32_e32 v58, v42
	v_pk_mul_f32 v[42:43], v[54:55], v[44:45]
	v_mov_b32_e32 v60, v50
	v_pk_mul_f32 v[50:51], v[56:57], v[52:53]
	v_pk_fma_f32 v[42:43], v[34:35], v[58:59], v[42:43] neg_lo:[0,0,1] neg_hi:[0,0,1]
	v_pk_fma_f32 v[50:51], v[36:37], v[60:61], v[50:51] neg_lo:[0,0,1] neg_hi:[0,0,1]
	v_cvt_pk_bf16_f32 v42, v42, v43
	v_cvt_pk_bf16_f32 v43, v50, v51
	v_pk_mul_f32 v[50:51], v[54:55], v[58:59]
	s_nop 0
	v_pk_fma_f32 v[34:35], v[34:35], v[44:45], v[50:51]
	v_pk_mul_f32 v[44:45], v[56:57], v[60:61]
	v_cvt_pk_bf16_f32 v34, v34, v35
	v_pk_fma_f32 v[36:37], v[36:37], v[52:53], v[44:45]
	s_nop 0
	v_cvt_pk_bf16_f32 v35, v36, v37
	v_add_u32_e32 v36, v63, v71
	ds_write_b64 v36, v[42:43]
	v_add_u32_e32 v36, v63, v100
	ds_write_b64 v36, v[34:35]
	ds_read_b128 v[34:37], v62 offset:128
	ds_read_b128 v[42:45], v62 offset:144
	s_waitcnt lgkmcnt(1)
	v_mov_b32_e32 v51, v36
	v_mov_b32_e32 v36, v35
	s_waitcnt lgkmcnt(0)
	v_mov_b32_e32 v53, v44
	v_mov_b32_e32 v44, v43
	v_mov_b32_e32 v50, v34
	v_pk_mul_f32 v[34:35], v[46:47], v[36:37]
	v_mov_b32_e32 v52, v42
	v_pk_mul_f32 v[42:43], v[48:49], v[44:45]
	v_pk_fma_f32 v[34:35], v[26:27], v[50:51], v[34:35] neg_lo:[0,0,1] neg_hi:[0,0,1]
	v_pk_fma_f32 v[42:43], v[28:29], v[52:53], v[42:43] neg_lo:[0,0,1] neg_hi:[0,0,1]
	v_cvt_pk_bf16_f32 v34, v34, v35
	v_cvt_pk_bf16_f32 v35, v42, v43
	v_pk_mul_f32 v[42:43], v[46:47], v[50:51]
	v_add_u32_e32 v46, v77, v73
	v_pk_fma_f32 v[26:27], v[26:27], v[36:37], v[42:43]
	v_pk_mul_f32 v[36:37], v[48:49], v[52:53]
	v_cvt_pk_bf16_f32 v26, v26, v27
	v_pk_fma_f32 v[28:29], v[28:29], v[44:45], v[36:37]
	v_add_u32_e32 v47, 0xd800, v70
	v_cvt_pk_bf16_f32 v27, v28, v29
	v_add_u32_e32 v28, v63, v83
	ds_write_b64 v28, v[34:35]
	v_add_u32_e32 v28, v63, v94
	ds_write_b64 v28, v[26:27]
	ds_read_b128 v[26:29], v46
	ds_read_b128 v[34:37], v46 offset:16
	s_waitcnt lgkmcnt(1)
	v_mov_b32_e32 v43, v28
	v_mov_b32_e32 v28, v27
	s_waitcnt lgkmcnt(0)
	v_mov_b32_e32 v45, v36
	v_mov_b32_e32 v36, v35
	v_mov_b32_e32 v42, v26
	v_pk_mul_f32 v[26:27], v[38:39], v[28:29]
	v_mov_b32_e32 v44, v34
	v_pk_mul_f32 v[34:35], v[40:41], v[36:37]
	v_pk_fma_f32 v[26:27], v[22:23], v[42:43], v[26:27] neg_lo:[0,0,1] neg_hi:[0,0,1]
	v_pk_fma_f32 v[34:35], v[24:25], v[44:45], v[34:35] neg_lo:[0,0,1] neg_hi:[0,0,1]
	v_cvt_pk_bf16_f32 v26, v26, v27
	v_cvt_pk_bf16_f32 v27, v34, v35
	v_pk_mul_f32 v[34:35], v[38:39], v[42:43]
	s_nop 0
	v_pk_fma_f32 v[22:23], v[22:23], v[28:29], v[34:35]
	v_pk_mul_f32 v[28:29], v[40:41], v[44:45]
	v_cvt_pk_bf16_f32 v22, v22, v23
	v_pk_fma_f32 v[24:25], v[24:25], v[36:37], v[28:29]
	s_nop 0
	v_cvt_pk_bf16_f32 v23, v24, v25
	v_add_u32_e32 v24, v47, v71
	ds_write_b64 v24, v[26:27]
	v_add_u32_e32 v24, v47, v100
	ds_write_b64 v24, v[22:23]
	ds_read_b128 v[22:25], v46 offset:128
	ds_read_b128 v[26:29], v46 offset:144
	v_lshlrev_b32_e32 v46, 2, v82
	v_or_b32_e32 v42, 2, v46
	s_waitcnt lgkmcnt(1)
	v_mov_b32_e32 v35, v24
	v_mov_b32_e32 v24, v23
	s_waitcnt lgkmcnt(0)
	v_mov_b32_e32 v37, v28
	v_mov_b32_e32 v28, v27
	v_mov_b32_e32 v34, v22
	v_pk_mul_f32 v[22:23], v[30:31], v[24:25]
	v_mov_b32_e32 v36, v26
	v_pk_mul_f32 v[26:27], v[32:33], v[28:29]
	v_pk_fma_f32 v[22:23], v[18:19], v[34:35], v[22:23] neg_lo:[0,0,1] neg_hi:[0,0,1]
	v_pk_fma_f32 v[26:27], v[20:21], v[36:37], v[26:27] neg_lo:[0,0,1] neg_hi:[0,0,1]
	v_cvt_pk_bf16_f32 v22, v22, v23
	v_cvt_pk_bf16_f32 v23, v26, v27
	v_pk_mul_f32 v[26:27], v[30:31], v[34:35]
	s_nop 0
	v_pk_fma_f32 v[18:19], v[18:19], v[24:25], v[26:27]
	v_pk_mul_f32 v[24:25], v[32:33], v[36:37]
	v_cvt_pk_bf16_f32 v18, v18, v19
	v_pk_fma_f32 v[20:21], v[20:21], v[28:29], v[24:25]
	v_bitop3_b32 v27, v81, v46, 4 bitop3:0x72
	v_cvt_pk_bf16_f32 v19, v20, v21
	v_add_u32_e32 v20, v47, v83
	ds_write_b64 v20, v[22:23]
	v_add_u32_e32 v20, v47, v94
	ds_write_b64 v20, v[18:19]
	v_and_b32_e32 v18, 0xfffffcf, v78
	v_mul_lo_u32 v18, v18, s10
	v_add_u32_e32 v26, 0, v18
	v_and_or_b32 v18, v46, 4, v81
	v_lshl_add_u32 v18, v18, 4, v26
	s_waitcnt lgkmcnt(0)
	s_barrier
	ds_read_b128 v[18:21], v18
	v_lshl_add_u32 v26, v27, 4, v26
	ds_read_b128 v[26:29], v26
	s_waitcnt vmcnt(3) lgkmcnt(1)
	v_mfma_f32_16x16x32_bf16 v[22:25], v[18:21], v[10:13], 0
	v_or_b32_e32 v47, 4, v81
	s_waitcnt vmcnt(1)
	v_mfma_f32_16x16x32_bf16 v[18:21], v[18:21], v[14:17], 0
	s_waitcnt lgkmcnt(0)
	v_mfma_f32_16x16x32_bf16 v[38:41], v[26:29], v[6:9], v[22:25]
	s_waitcnt vmcnt(0)
	v_mfma_f32_16x16x32_bf16 v[34:37], v[26:29], v[2:5], v[18:21]
	v_or_b32_e32 v26, 1, v46
	v_or_b32_e32 v46, 3, v46
	s_nop 1
	v_lshl_or_b32 v18, v26, 4, v80
	v_mul_lo_u32 v18, v18, s10
	v_add_u32_e32 v27, 0, v18
	v_bitop3_b32 v18, v26, v81, 5 bitop3:0x6c
	v_lshl_add_u32 v18, v18, 4, v27
	ds_read_b128 v[18:21], v18
	v_bitop3_b32 v26, v26, v47, 5 bitop3:0x6c
	v_lshl_add_u32 v26, v26, 4, v27
	ds_read_b128 v[26:29], v26
	s_waitcnt lgkmcnt(1)
	v_mfma_f32_16x16x32_bf16 v[22:25], v[18:21], v[10:13], 0
	v_mfma_f32_16x16x32_bf16 v[18:21], v[18:21], v[14:17], 0
	s_waitcnt lgkmcnt(0)
	v_mfma_f32_16x16x32_bf16 v[30:33], v[26:29], v[6:9], v[22:25]
	v_mfma_f32_16x16x32_bf16 v[26:29], v[26:29], v[2:5], v[18:21]
	s_nop 4
	v_lshl_or_b32 v18, v42, 4, v80
	v_mul_lo_u32 v18, v18, s10
	v_add_u32_e32 v43, 0, v18
	v_bitop3_b32 v18, v42, v81, 6 bitop3:0x6c
	v_lshl_add_u32 v18, v18, 4, v43
	ds_read_b128 v[18:21], v18
	v_bitop3_b32 v42, v42, v47, 6 bitop3:0x6c
	v_lshl_add_u32 v42, v42, 4, v43
	ds_read_b128 v[42:45], v42
	s_waitcnt lgkmcnt(1)
	v_mfma_f32_16x16x32_bf16 v[22:25], v[18:21], v[10:13], 0
	v_mfma_f32_16x16x32_bf16 v[18:21], v[18:21], v[14:17], 0
	s_waitcnt lgkmcnt(0)
	v_mfma_f32_16x16x32_bf16 v[22:25], v[42:45], v[6:9], v[22:25]
	v_mfma_f32_16x16x32_bf16 v[18:21], v[42:45], v[2:5], v[18:21]
	v_lshl_or_b32 v42, v46, 4, v80
	v_mul_lo_u32 v42, v42, s10
	v_add_u32_e32 v48, 0, v42
	v_bitop3_b32 v42, v46, v81, 7 bitop3:0x6c
	v_lshl_add_u32 v42, v42, 4, v48
	ds_read_b128 v[42:45], v42
	s_waitcnt lgkmcnt(0)
	v_mfma_f32_16x16x32_bf16 v[10:13], v[42:45], v[10:13], 0
	v_mfma_f32_16x16x32_bf16 v[14:17], v[42:45], v[14:17], 0
	v_bitop3_b32 v42, v46, v47, 7 bitop3:0x6c
	v_lshl_add_u32 v42, v42, 4, v48
	ds_read_b128 v[42:45], v42
	s_waitcnt lgkmcnt(0)
	v_mfma_f32_16x16x32_bf16 v[6:9], v[42:45], v[6:9], v[10:13]
	s_nop 2
	v_and_b32_e32 v13, 64, v1
	v_lshlrev_b32_e32 v10, 3, v82
	v_xor_b32_e32 v11, 16, v1
	v_add_u32_e32 v13, 64, v13
	v_add3_u32 v10, v10, s1, v79
	v_cmp_lt_i32_e32 vcc, v11, v13
	v_or_b32_e32 v10, v10, v76
	v_mfma_f32_16x16x32_bf16 v[2:5], v[42:45], v[2:5], v[14:17]
	v_cndmask_b32_e32 v11, v1, v11, vcc
	s_lshl_b32 s1, s7, 2
	v_bfe_u32 v12, v78, 4, 1
	v_lshlrev_b32_e32 v14, 2, v11
	v_pk_mul_f32 v[16:17], v[38:39], s[88:89] op_sel_hi:[1,0]
	v_pk_mul_f32 v[38:39], v[40:41], s[88:89] op_sel_hi:[1,0]
	v_ashrrev_i32_e32 v11, 31, v10
	v_cvt_pk_bf16_f32 v16, v16, v17
	v_cvt_pk_bf16_f32 v17, v38, v39
	v_lshlrev_b64 v[38:39], 11, v[10:11]
	s_add_u32 s22, s24, s1
	v_lshl_add_u64 v[38:39], s[84:85], 0, v[38:39]
	s_mov_b32 s1, s69
	v_lshl_add_u64 v[38:39], v[38:39], 0, s[0:1]
	v_lshlrev_b32_e32 v98, 3, v12
	v_lshl_add_u64 v[38:39], v[38:39], 0, v[98:99]
	s_mov_b32 s0, 0x1b00000
	v_add_co_u32_e32 v38, vcc, s0, v38
	v_and_b32_e32 v15, 0xffff0000, v16
	s_nop 0
	v_addc_co_u32_e32 v39, vcc, 0, v39, vcc
	global_store_dwordx2 v[38:39], v[16:17], off offset:1024
	v_lshlrev_b32_e32 v13, 16, v16
	v_mul_f32_e32 v15, v15, v15
	v_and_b32_e32 v16, 0xffff0000, v17
	v_fmac_f32_e32 v15, v13, v13
	v_lshlrev_b32_e32 v13, 16, v17
	v_mul_f32_e32 v16, v16, v16
	v_fmac_f32_e32 v16, v13, v13
	v_add_f32_e32 v13, v15, v16
	v_mov_b32_e32 v15, v13
	s_nop 1
	v_permlane16_swap_b32_e32 v13, v15
	v_cmp_eq_u32_e64 s[38:39], 0, v12
	s_addc_u32 s23, s25, 0
	s_and_saveexec_b64 s[0:1], s[38:39]
	s_cbranch_execz .LBB0_805
	v_lshlrev_b64 v[16:17], 7, v[10:11]
	s_waitcnt lgkmcnt(0)
	v_add_f32_e32 v13, v13, v15
	v_lshl_add_u64 v[16:17], s[22:23], 0, v[16:17]
	global_store_dword v[16:17], v13, off
